# speedup vs baseline: 1.0004x; 1.0004x over previous
;     DI void operator()(const pg8::f32x4 (&acc)[2][2][4][2], const pg8::Unit& u, int wr, int wc, int fr, int fq) const {
;     ...
;                 const int r = u.pm * 256 + ai * 128 + wr * 64 + m * 16 + fr;
;                 const int pi = r < MPROMPT ? (r & 2047) : 2048;
;                 const int t = r & 2047;
; #pragma unroll
;                 for (int bj = 0; bj < 2; ++bj) {
;                     const int c0 = pn * 256 + bj * 128 + wc * 32 + 8 * fq;
;                     const f32x4 v0 = acc[ai][bj][m][0] * rsc[ai][m], v1 = acc[ai][bj][m][1] * rsc[ai][m];
;                     if (pn < 4 || (pn == 4 && bj == 0)) {
;                         const int i4 = ((c0 & 63) >> 3) * 4;
;                         const f32x4 cs = *(const f32x4*)(rc + pi * 32 + i4), sn = *(const f32x4*)(rs + pi * 32 + i4);
;                         f32x4 o1 = v0 * cs - v1 * sn, o2 = v1 * cs + v0 * sn;
.LBB0_169:
	s_ashr_i32 s7, s6, 4
	s_and_b32 s7, s7, 0xffffff80
	s_addk_i32 s7, 0xf880
	v_add_u32_e32 v164, s7, v149
	v_lshlrev_b32_e32 v149, 5, v149
	v_lshl_add_u32 v160, v168, 7, v247
	v_ashrrev_i32_e32 v165, 31, v164
	v_cndmask_b32_e64 v149, v248, v149, s[42:43]
	v_lshlrev_b64 v[174:175], 8, v[168:169]
	v_lshlrev_b64 v[172:173], 9, v[160:161]
	v_lshlrev_b64 v[178:179], 9, v[164:165]
	s_andn2_b64 vcc, exec, s[38:39]
	v_lshlrev_b32_e32 v160, 2, v149
	s_cbranch_vccnz .LBB0_176
	v_lshl_add_u64 v[164:165], v[140:141], 0, v[160:161]
	s_cmp_lt_u32 s6, 0x2000
	s_cselect_b32 s100, 0x800, 0
	v_mov_b32_e32 v235, 0
	v_mov_b32_e32 v237, 0
	v_mov_b32_e32 v239, 0
	v_add_u32_e32 v234, s100, v160
	v_add_u32_e32 v236, s100, v234
	v_add_u32_e32 v238, s100, v236
	v_lshl_add_u64 v[240:241], v[140:141], 0, v[160:161]
	global_load_dwordx4 v[194:197], v[240:241], off
	v_lshl_add_u64 v[240:241], v[138:139], 0, v[160:161]
	global_load_dwordx4 v[198:201], v[240:241], off
	v_lshl_add_u64 v[240:241], v[140:141], 0, v[234:235]
	global_load_dwordx4 v[202:205], v[240:241], off
	v_lshl_add_u64 v[240:241], v[138:139], 0, v[234:235]
	global_load_dwordx4 v[206:209], v[240:241], off
	v_lshl_add_u64 v[240:241], v[140:141], 0, v[236:237]
	global_load_dwordx4 v[210:213], v[240:241], off
	v_lshl_add_u64 v[240:241], v[138:139], 0, v[236:237]
	global_load_dwordx4 v[214:217], v[240:241], off
	v_lshl_add_u64 v[240:241], v[140:141], 0, v[238:239]
	global_load_dwordx4 v[218:221], v[240:241], off
	v_lshl_add_u64 v[240:241], v[138:139], 0, v[238:239]
	global_load_dwordx4 v[222:225], v[240:241], off
	v_lshl_add_u64 v[164:165], v[138:139], 0, v[160:161]
	s_mov_b64 s[14:15], -1
	s_and_b64 vcc, exec, s[46:47]
	s_waitcnt vmcnt(0)
	v_mov_b64_e32 v[186:187], v[194:195]
	v_mov_b64_e32 v[188:189], v[196:197]
	v_mov_b64_e32 v[190:191], v[198:199]
	v_mov_b64_e32 v[192:193], v[200:201]
	v_pk_mul_f32 v[164:165], v[122:123], v[188:189]
	v_pk_mul_f32 v[180:181], v[120:121], v[186:187]
	v_pk_mul_f32 v[188:189], v[126:127], v[188:189]
	v_pk_mul_f32 v[186:187], v[124:125], v[186:187]
	v_pk_fma_f32 v[126:127], v[126:127], v[192:193], v[164:165] neg_lo:[0,0,1] neg_hi:[0,0,1]
	v_pk_fma_f32 v[124:125], v[124:125], v[190:191], v[180:181] neg_lo:[0,0,1] neg_hi:[0,0,1]
	v_pk_fma_f32 v[122:123], v[122:123], v[192:193], v[188:189]
	v_pk_fma_f32 v[120:121], v[120:121], v[190:191], v[186:187]
	s_cbranch_vccz .LBB0_174
	v_add_u32_e32 v149, 0xfffffc00, v146
	v_readlane_b32 s14, v253, 19
	v_readlane_b32 s15, v253, 20
	v_and_b32_e32 v186, 0xffffffc0, v149
	v_ashrrev_i32_e32 v187, 31, v186
	v_lshl_add_u64 v[180:181], s[14:15], 0, v[174:175]
	v_lshl_add_u64 v[180:181], v[186:187], 1, v[180:181]
	v_lshlrev_b32_e32 v186, 1, v136
	v_mov_b32_e32 v187, v161
	v_lshl_add_u64 v[180:181], v[180:181], 0, v[186:187]
	v_cvt_pk_bf16_f32 v186, v124, v125
	v_cvt_pk_bf16_f32 v187, v126, v127
	v_ashrrev_i32_e32 v164, 6, v149
	global_store_dwordx2 v[180:181], v[186:187], off
	v_cvt_pk_bf16_f32 v186, v120, v121
	v_cvt_pk_bf16_f32 v187, v122, v123
	global_store_dwordx2 v[180:181], v[186:187], off offset:64
	v_ashrrev_i32_e32 v165, 31, v164
	v_lshl_add_u64 v[180:181], s[56:57], 0, v[172:173]
	v_lshl_add_u64 v[186:187], s[52:53], 0, v[178:179]
	v_cndmask_b32_e64 v149, 0, 1, s[44:45]
	v_cndmask_b32_e64 v151, 0, 1, s[70:71]
	v_lshlrev_b64 v[164:165], 8, v[164:165]
	v_cndmask_b32_e64 v181, v181, v187, s[42:43]
	v_cndmask_b32_e64 v180, v180, v186, s[42:43]
	v_cndmask_b32_e64 v149, v151, v149, s[42:43]
	v_and_b32_e32 v149, 1, v149
	v_lshl_add_u64 v[180:181], v[180:181], 0, v[164:165]
	v_cmp_eq_u32_e32 vcc, 1, v149
	v_cmp_ne_u64_e64 s[38:39], 0, v[180:181]
	s_and_b64 s[24:25], vcc, s[38:39]
	s_and_saveexec_b64 s[14:15], s[24:25]
	s_cbranch_execz .LBB0_173
	v_lshlrev_b32_e32 v164, 2, v136
	v_mov_b32_e32 v165, v161
	v_lshl_add_u64 v[164:165], v[180:181], 0, v[164:165]
	global_store_dwordx4 v[164:165], v[124:127], off
	global_store_dwordx4 v[164:165], v[120:123], off offset:128

; DI u32x2 pack4(const f32x4 a) { u32x2 w; w.x = cvt_pk_bf16(a[0], a[1]); w.y = cvt_pk_bf16(a[2], a[3]); return w; }
;     DI void operator()(const pg8::f32x4 (&acc)[2][2][4][2], const pg8::Unit& u, int wr, int wc, int fr, int fq) const {
;     ...
;                     if (pn < 4 || (pn == 4 && bj == 0)) {
;                         const int i4 = ((c0 & 63) >> 3) * 4;
;                         const f32x4 cs = *(const f32x4*)(rc + pi * 32 + i4), sn = *(const f32x4*)(rs + pi * 32 + i4);
;                         f32x4 o1 = v0 * cs - v1 * sn, o2 = v1 * cs + v0 * sn;
;                         if (pn < 4) {
;                             o1 = o1 * 0.125f; o2 = o2 * 0.125f;
;                             bf16_t* dst = Q + (size_t)r * AW + (c0 & ~63) + i4;
;                             *(u32x2*)dst = pack4(o1); *(u32x2*)(dst + 32) = pack4(o2);
.LBB0_184:
	v_and_b32_e32 v122, 0xffffffc0, v120
	s_andn2_b64 vcc, exec, s[14:15]
	v_ashrrev_i32_e32 v123, 31, v122
	v_lshlrev_b32_e32 v124, 1, v136
	s_cbranch_vccnz .LBB0_186
	v_lshl_add_u64 v[126:127], v[140:141], 0, v[160:161]
	v_mov_b64_e32 v[172:173], v[194:195]
	v_mov_b64_e32 v[174:175], v[196:197]
	v_lshl_add_u64 v[126:127], v[138:139], 0, v[160:161]
	v_mov_b64_e32 v[176:177], v[198:199]
	v_mov_b64_e32 v[178:179], v[200:201]
	v_lshl_add_u64 v[126:127], s[22:23], 0, v[170:171]
	v_mov_b32_e32 v125, v161
	v_lshl_add_u64 v[126:127], v[122:123], 1, v[126:127]
	v_lshl_add_u64 v[126:127], v[126:127], 0, v[124:125]
	v_pk_mul_f32 v[170:171], v[116:117], v[172:173]
	v_pk_mul_f32 v[172:173], v[112:113], v[172:173]
	v_pk_mul_f32 v[164:165], v[118:119], v[174:175]
	v_pk_mul_f32 v[174:175], v[114:115], v[174:175]
	v_pk_fma_f32 v[112:113], v[112:113], v[176:177], v[170:171]
	v_pk_fma_f32 v[116:117], v[116:117], v[176:177], v[172:173] neg_lo:[0,0,1] neg_hi:[0,0,1]
	v_pk_fma_f32 v[114:115], v[114:115], v[178:179], v[164:165]
	v_pk_fma_f32 v[118:119], v[118:119], v[178:179], v[174:175] neg_lo:[0,0,1] neg_hi:[0,0,1]
	v_pk_mul_f32 v[116:117], v[116:117], s[16:17] op_sel_hi:[1,0]
	v_pk_mul_f32 v[112:113], v[112:113], s[16:17] op_sel_hi:[1,0]
	v_pk_mul_f32 v[118:119], v[118:119], s[16:17] op_sel_hi:[1,0]
	v_pk_mul_f32 v[114:115], v[114:115], s[16:17] op_sel_hi:[1,0]
	v_cvt_pk_bf16_f32 v116, v116, v117
	v_cvt_pk_bf16_f32 v117, v118, v119
	global_store_dwordx2 v[126:127], v[116:117], off
	v_cvt_pk_bf16_f32 v112, v112, v113
	v_cvt_pk_bf16_f32 v113, v114, v115
	global_store_dwordx2 v[126:127], v[112:113], off offset:64

; DI u32x2 pack4(const f32x4 a) { u32x2 w; w.x = cvt_pk_bf16(a[0], a[1]); w.y = cvt_pk_bf16(a[2], a[3]); return w; }
;     DI void operator()(const pg8::f32x4 (&acc)[2][2][4][2], const pg8::Unit& u, int wr, int wc, int fr, int fq) const {
;     ...
;                 const int r = u.pm * 256 + ai * 128 + wr * 64 + m * 16 + fr;
;                 const int pi = r < MPROMPT ? (r & 2047) : 2048;
;                 const int t = r & 2047;
; #pragma unroll
;                 for (int bj = 0; bj < 2; ++bj) {
;                     const int c0 = pn * 256 + bj * 128 + wc * 32 + 8 * fq;
;                     const f32x4 v0 = acc[ai][bj][m][0] * rsc[ai][m], v1 = acc[ai][bj][m][1] * rsc[ai][m];
;                     if (pn < 4 || (pn == 4 && bj == 0)) {
;                         const int i4 = ((c0 & 63) >> 3) * 4;
;                         const f32x4 cs = *(const f32x4*)(rc + pi * 32 + i4), sn = *(const f32x4*)(rs + pi * 32 + i4);
;                         f32x4 o1 = v0 * cs - v1 * sn, o2 = v1 * cs + v0 * sn;
;                         if (pn < 4) {
;                             o1 = o1 * 0.125f; o2 = o2 * 0.125f;
;                             bf16_t* dst = Q + (size_t)r * AW + (c0 & ~63) + i4;
;                             *(u32x2*)dst = pack4(o1); *(u32x2*)(dst + 32) = pack4(o2);
;                         } else {
;                             const int kvh = (c0 - 1024) >> 6;
;                             bf16_t* dst = Kb + (size_t)r * KVC + kvh * 64 + i4;
;                             *(u32x2*)dst = pack4(o1); *(u32x2*)(dst + 32) = pack4(o2);
;                             float* fo = nullptr;
;                             if (r < MPROMPT) { if (t >= SEQ - 128) fo = kp + ((size_t)((r >> 11) * 128 + (t - (SEQ - 128))) * 2 + kvh) * 64 + i4; }
;                             else if (r < MVALID) fo = ks + ((size_t)((r - MPROMPT) * 128 + 127) * 2 + kvh) * 64 + i4;
;                             if (fo) { *(f32x4*)fo = o1; *(f32x4*)(fo + 32) = o2; }
.LBB0_188:
	s_nop 1
	v_add_u32_e32 v118, s7, v121
	v_lshlrev_b32_e32 v121, 5, v121
	v_lshl_add_u32 v160, v114, 7, v247
	v_ashrrev_i32_e32 v119, 31, v118
	v_cndmask_b32_e64 v121, v248, v121, s[44:45]
	v_lshlrev_b64 v[116:117], 8, v[114:115]
	v_lshlrev_b64 v[114:115], 9, v[160:161]
	v_lshlrev_b64 v[118:119], 9, v[118:119]
	s_andn2_b64 vcc, exec, s[14:15]
	v_lshlrev_b32_e32 v160, 2, v121
	s_cbranch_vccnz .LBB0_195
	v_lshl_add_u64 v[126:127], v[140:141], 0, v[160:161]
	v_mov_b64_e32 v[168:169], v[202:203]
	v_mov_b64_e32 v[170:171], v[204:205]
	v_lshl_add_u64 v[126:127], v[138:139], 0, v[160:161]
	v_mov_b64_e32 v[172:173], v[206:207]
	v_mov_b64_e32 v[174:175], v[208:209]
	s_and_b64 vcc, exec, s[40:41]
	s_mov_b64 s[14:15], -1
	v_pk_mul_f32 v[126:127], v[106:107], v[170:171]
	v_pk_mul_f32 v[164:165], v[104:105], v[168:169]
	v_pk_mul_f32 v[170:171], v[110:111], v[170:171]
	v_pk_mul_f32 v[168:169], v[108:109], v[168:169]
	v_pk_fma_f32 v[110:111], v[110:111], v[174:175], v[126:127] neg_lo:[0,0,1] neg_hi:[0,0,1]
	v_pk_fma_f32 v[108:109], v[108:109], v[172:173], v[164:165] neg_lo:[0,0,1] neg_hi:[0,0,1]
	v_pk_fma_f32 v[106:107], v[106:107], v[174:175], v[170:171]
	v_pk_fma_f32 v[104:105], v[104:105], v[172:173], v[168:169]
	s_cbranch_vccnz .LBB0_193
	v_add_u32_e32 v121, 0xfffffc00, v146
	v_readlane_b32 s14, v253, 19
	v_readlane_b32 s15, v253, 20
	v_and_b32_e32 v168, 0xffffffc0, v121
	v_ashrrev_i32_e32 v169, 31, v168
	v_lshl_add_u64 v[164:165], s[14:15], 0, v[116:117]
	v_lshl_add_u64 v[164:165], v[168:169], 1, v[164:165]
	v_mov_b32_e32 v125, v161
	v_lshl_add_u64 v[164:165], v[164:165], 0, v[124:125]
	v_cvt_pk_bf16_f32 v168, v108, v109
	v_cvt_pk_bf16_f32 v169, v110, v111
	v_ashrrev_i32_e32 v126, 6, v121
	global_store_dwordx2 v[164:165], v[168:169], off
	v_cvt_pk_bf16_f32 v168, v104, v105
	v_cvt_pk_bf16_f32 v169, v106, v107
	global_store_dwordx2 v[164:165], v[168:169], off offset:64
	v_ashrrev_i32_e32 v127, 31, v126
	v_lshl_add_u64 v[164:165], s[52:53], 0, v[118:119]
	v_lshl_add_u64 v[168:169], s[56:57], 0, v[114:115]
	v_cndmask_b32_e64 v121, 0, 1, s[46:47]
	v_cndmask_b32_e64 v125, 0, 1, s[70:71]
	v_lshlrev_b64 v[126:127], 8, v[126:127]
	v_cndmask_b32_e64 v165, v169, v165, s[44:45]
	v_cndmask_b32_e64 v164, v168, v164, s[44:45]
	v_cndmask_b32_e64 v121, v125, v121, s[44:45]
	v_and_b32_e32 v121, 1, v121
	v_lshl_add_u64 v[126:127], v[164:165], 0, v[126:127]
	v_cmp_eq_u32_e32 vcc, 1, v121
	v_cmp_ne_u64_e64 s[48:49], 0, v[126:127]
	s_and_b64 s[24:25], vcc, s[48:49]
	s_and_saveexec_b64 s[14:15], s[24:25]
	s_cbranch_execz .LBB0_192
	v_lshlrev_b32_e32 v164, 2, v136
	v_mov_b32_e32 v165, v161
	v_lshl_add_u64 v[126:127], v[126:127], 0, v[164:165]
	global_store_dwordx4 v[126:127], v[108:111], off
	global_store_dwordx4 v[126:127], v[104:107], off offset:128

; DI u32x2 pack4(const f32x4 a) { u32x2 w; w.x = cvt_pk_bf16(a[0], a[1]); w.y = cvt_pk_bf16(a[2], a[3]); return w; }
;     DI void operator()(const pg8::f32x4 (&acc)[2][2][4][2], const pg8::Unit& u, int wr, int wc, int fr, int fq) const {
;     ...
;                     if (pn < 4 || (pn == 4 && bj == 0)) {
;                         const int i4 = ((c0 & 63) >> 3) * 4;
;                         const f32x4 cs = *(const f32x4*)(rc + pi * 32 + i4), sn = *(const f32x4*)(rs + pi * 32 + i4);
;                         f32x4 o1 = v0 * cs - v1 * sn, o2 = v1 * cs + v0 * sn;
;                         if (pn < 4) {
;                             o1 = o1 * 0.125f; o2 = o2 * 0.125f;
;                             bf16_t* dst = Q + (size_t)r * AW + (c0 & ~63) + i4;
;                             *(u32x2*)dst = pack4(o1); *(u32x2*)(dst + 32) = pack4(o2);
.LBB0_203:
	s_andn2_b64 vcc, exec, s[14:15]
	s_cbranch_vccnz .LBB0_205
	v_lshl_add_u64 v[104:105], v[140:141], 0, v[160:161]
	v_mov_b64_e32 v[104:105], v[202:203]
	v_mov_b64_e32 v[106:107], v[204:205]
	v_lshl_add_u64 v[108:109], v[138:139], 0, v[160:161]
	v_mov_b64_e32 v[108:109], v[206:207]
	v_mov_b64_e32 v[110:111], v[208:209]
	v_lshl_add_u64 v[112:113], s[22:23], 0, v[112:113]
	v_mov_b32_e32 v125, v161
	v_lshl_add_u64 v[112:113], v[122:123], 1, v[112:113]
	v_lshl_add_u64 v[112:113], v[112:113], 0, v[124:125]
	v_pk_mul_f32 v[116:117], v[100:101], v[104:105]
	v_pk_mul_f32 v[104:105], v[96:97], v[104:105]
	v_pk_mul_f32 v[114:115], v[102:103], v[106:107]
	v_pk_mul_f32 v[106:107], v[98:99], v[106:107]
	v_pk_fma_f32 v[96:97], v[96:97], v[108:109], v[116:117]
	v_pk_fma_f32 v[100:101], v[100:101], v[108:109], v[104:105] neg_lo:[0,0,1] neg_hi:[0,0,1]
	v_pk_fma_f32 v[98:99], v[98:99], v[110:111], v[114:115]
	v_pk_fma_f32 v[102:103], v[102:103], v[110:111], v[106:107] neg_lo:[0,0,1] neg_hi:[0,0,1]
	v_pk_mul_f32 v[100:101], v[100:101], s[16:17] op_sel_hi:[1,0]
	v_pk_mul_f32 v[96:97], v[96:97], s[16:17] op_sel_hi:[1,0]
	v_pk_mul_f32 v[102:103], v[102:103], s[16:17] op_sel_hi:[1,0]
	v_pk_mul_f32 v[98:99], v[98:99], s[16:17] op_sel_hi:[1,0]
	v_cvt_pk_bf16_f32 v100, v100, v101
	v_cvt_pk_bf16_f32 v101, v102, v103
	global_store_dwordx2 v[112:113], v[100:101], off
	v_cvt_pk_bf16_f32 v96, v96, v97
	v_cvt_pk_bf16_f32 v97, v98, v99
	global_store_dwordx2 v[112:113], v[96:97], off offset:64

; DI u32x2 pack4(const f32x4 a) { u32x2 w; w.x = cvt_pk_bf16(a[0], a[1]); w.y = cvt_pk_bf16(a[2], a[3]); return w; }
;     DI void operator()(const pg8::f32x4 (&acc)[2][2][4][2], const pg8::Unit& u, int wr, int wc, int fr, int fq) const {
;     ...
;                 const int r = u.pm * 256 + ai * 128 + wr * 64 + m * 16 + fr;
;                 const int pi = r < MPROMPT ? (r & 2047) : 2048;
;                 const int t = r & 2047;
; #pragma unroll
;                 for (int bj = 0; bj < 2; ++bj) {
;                     const int c0 = pn * 256 + bj * 128 + wc * 32 + 8 * fq;
;                     const f32x4 v0 = acc[ai][bj][m][0] * rsc[ai][m], v1 = acc[ai][bj][m][1] * rsc[ai][m];
;                     if (pn < 4 || (pn == 4 && bj == 0)) {
;                         const int i4 = ((c0 & 63) >> 3) * 4;
;                         const f32x4 cs = *(const f32x4*)(rc + pi * 32 + i4), sn = *(const f32x4*)(rs + pi * 32 + i4);
;                         f32x4 o1 = v0 * cs - v1 * sn, o2 = v1 * cs + v0 * sn;
;                         if (pn < 4) {
;                             o1 = o1 * 0.125f; o2 = o2 * 0.125f;
;                             bf16_t* dst = Q + (size_t)r * AW + (c0 & ~63) + i4;
;                             *(u32x2*)dst = pack4(o1); *(u32x2*)(dst + 32) = pack4(o2);
;                         } else {
;                             const int kvh = (c0 - 1024) >> 6;
;                             bf16_t* dst = Kb + (size_t)r * KVC + kvh * 64 + i4;
;                             *(u32x2*)dst = pack4(o1); *(u32x2*)(dst + 32) = pack4(o2);
;                             float* fo = nullptr;
;                             if (r < MPROMPT) { if (t >= SEQ - 128) fo = kp + ((size_t)((r >> 11) * 128 + (t - (SEQ - 128))) * 2 + kvh) * 64 + i4; }
;                             else if (r < MVALID) fo = ks + ((size_t)((r - MPROMPT) * 128 + 127) * 2 + kvh) * 64 + i4;
;                             if (fo) { *(f32x4*)fo = o1; *(f32x4*)(fo + 32) = o2; }
.LBB0_207:
	s_nop 1
	v_add_u32_e32 v102, s7, v104
	v_lshlrev_b32_e32 v104, 5, v104
	v_lshl_add_u32 v160, v98, 7, v247
	v_ashrrev_i32_e32 v103, 31, v102
	v_cndmask_b32_e64 v104, v248, v104, s[44:45]
	v_lshlrev_b64 v[100:101], 8, v[98:99]
	v_lshlrev_b64 v[98:99], 9, v[160:161]
	v_lshlrev_b64 v[102:103], 9, v[102:103]
	s_andn2_b64 vcc, exec, s[14:15]
	v_lshlrev_b32_e32 v160, 2, v104
	s_cbranch_vccnz .LBB0_214
	v_lshl_add_u64 v[104:105], v[140:141], 0, v[160:161]
	v_mov_b64_e32 v[104:105], v[210:211]
	v_mov_b64_e32 v[106:107], v[212:213]
	v_lshl_add_u64 v[108:109], v[138:139], 0, v[160:161]
	v_mov_b64_e32 v[108:109], v[214:215]
	v_mov_b64_e32 v[110:111], v[216:217]
	s_and_b64 vcc, exec, s[40:41]
	s_mov_b64 s[14:15], -1
	v_pk_mul_f32 v[112:113], v[90:91], v[106:107]
	v_pk_mul_f32 v[114:115], v[88:89], v[104:105]
	v_pk_mul_f32 v[106:107], v[94:95], v[106:107]
	v_pk_mul_f32 v[104:105], v[92:93], v[104:105]
	v_pk_fma_f32 v[94:95], v[94:95], v[110:111], v[112:113] neg_lo:[0,0,1] neg_hi:[0,0,1]
	v_pk_fma_f32 v[92:93], v[92:93], v[108:109], v[114:115] neg_lo:[0,0,1] neg_hi:[0,0,1]
	v_pk_fma_f32 v[90:91], v[90:91], v[110:111], v[106:107]
	v_pk_fma_f32 v[88:89], v[88:89], v[108:109], v[104:105]
	s_cbranch_vccnz .LBB0_212
	v_add_u32_e32 v105, 0xfffffc00, v146
	v_readlane_b32 s14, v253, 19
	v_readlane_b32 s15, v253, 20
	v_and_b32_e32 v108, 0xffffffc0, v105
	v_ashrrev_i32_e32 v109, 31, v108
	v_lshl_add_u64 v[106:107], s[14:15], 0, v[100:101]
	v_lshl_add_u64 v[106:107], v[108:109], 1, v[106:107]
	v_mov_b32_e32 v125, v161
	v_lshl_add_u64 v[106:107], v[106:107], 0, v[124:125]
	v_cvt_pk_bf16_f32 v108, v92, v93
	v_cvt_pk_bf16_f32 v109, v94, v95
	global_store_dwordx2 v[106:107], v[108:109], off
	v_cvt_pk_bf16_f32 v108, v88, v89
	v_cvt_pk_bf16_f32 v109, v90, v91
	v_ashrrev_i32_e32 v104, 6, v105
	global_store_dwordx2 v[106:107], v[108:109], off offset:64
	v_lshl_add_u64 v[106:107], s[52:53], 0, v[102:103]
	v_lshl_add_u64 v[108:109], s[56:57], 0, v[98:99]
	v_ashrrev_i32_e32 v105, 31, v104
	v_cndmask_b32_e64 v107, v109, v107, s[44:45]
	v_cndmask_b32_e64 v106, v108, v106, s[44:45]
	v_cndmask_b32_e64 v108, 0, 1, s[46:47]
	v_cndmask_b32_e64 v109, 0, 1, s[70:71]
	v_lshlrev_b64 v[104:105], 8, v[104:105]
	v_cndmask_b32_e64 v108, v109, v108, s[44:45]
	v_and_b32_e32 v108, 1, v108
	v_lshl_add_u64 v[104:105], v[106:107], 0, v[104:105]
	v_cmp_eq_u32_e32 vcc, 1, v108
	v_cmp_ne_u64_e64 s[48:49], 0, v[104:105]
	s_and_b64 s[24:25], vcc, s[48:49]
	s_and_saveexec_b64 s[14:15], s[24:25]
	s_cbranch_execz .LBB0_211
	v_lshlrev_b32_e32 v106, 2, v136
	v_mov_b32_e32 v107, v161
	v_lshl_add_u64 v[104:105], v[104:105], 0, v[106:107]
	global_store_dwordx4 v[104:105], v[92:95], off
	global_store_dwordx4 v[104:105], v[88:91], off offset:128

; DI u32x2 pack4(const f32x4 a) { u32x2 w; w.x = cvt_pk_bf16(a[0], a[1]); w.y = cvt_pk_bf16(a[2], a[3]); return w; }
;     DI void operator()(const pg8::f32x4 (&acc)[2][2][4][2], const pg8::Unit& u, int wr, int wc, int fr, int fq) const {
;     ...
;                     if (pn < 4 || (pn == 4 && bj == 0)) {
;                         const int i4 = ((c0 & 63) >> 3) * 4;
;                         const f32x4 cs = *(const f32x4*)(rc + pi * 32 + i4), sn = *(const f32x4*)(rs + pi * 32 + i4);
;                         f32x4 o1 = v0 * cs - v1 * sn, o2 = v1 * cs + v0 * sn;
;                         if (pn < 4) {
;                             o1 = o1 * 0.125f; o2 = o2 * 0.125f;
;                             bf16_t* dst = Q + (size_t)r * AW + (c0 & ~63) + i4;
;                             *(u32x2*)dst = pack4(o1); *(u32x2*)(dst + 32) = pack4(o2);
.LBB0_222:
	s_andn2_b64 vcc, exec, s[14:15]
	s_cbranch_vccnz .LBB0_224
	v_lshl_add_u64 v[88:89], v[140:141], 0, v[160:161]
	v_mov_b64_e32 v[88:89], v[210:211]
	v_mov_b64_e32 v[90:91], v[212:213]
	v_lshl_add_u64 v[92:93], v[138:139], 0, v[160:161]
	v_mov_b64_e32 v[92:93], v[214:215]
	v_mov_b64_e32 v[94:95], v[216:217]
	v_lshl_add_u64 v[96:97], s[22:23], 0, v[96:97]
	v_mov_b32_e32 v125, v161
	v_lshl_add_u64 v[96:97], v[122:123], 1, v[96:97]
	v_lshl_add_u64 v[96:97], v[96:97], 0, v[124:125]
	v_pk_mul_f32 v[100:101], v[84:85], v[88:89]
	v_pk_mul_f32 v[88:89], v[80:81], v[88:89]
	v_pk_mul_f32 v[98:99], v[86:87], v[90:91]
	v_pk_mul_f32 v[90:91], v[82:83], v[90:91]
	v_pk_fma_f32 v[80:81], v[80:81], v[92:93], v[100:101]
	v_pk_fma_f32 v[84:85], v[84:85], v[92:93], v[88:89] neg_lo:[0,0,1] neg_hi:[0,0,1]
	v_pk_fma_f32 v[82:83], v[82:83], v[94:95], v[98:99]
	v_pk_fma_f32 v[86:87], v[86:87], v[94:95], v[90:91] neg_lo:[0,0,1] neg_hi:[0,0,1]
	v_pk_mul_f32 v[84:85], v[84:85], s[16:17] op_sel_hi:[1,0]
	v_pk_mul_f32 v[80:81], v[80:81], s[16:17] op_sel_hi:[1,0]
	v_pk_mul_f32 v[86:87], v[86:87], s[16:17] op_sel_hi:[1,0]
	v_pk_mul_f32 v[82:83], v[82:83], s[16:17] op_sel_hi:[1,0]
	v_cvt_pk_bf16_f32 v84, v84, v85
	v_cvt_pk_bf16_f32 v85, v86, v87
	global_store_dwordx2 v[96:97], v[84:85], off
	v_cvt_pk_bf16_f32 v80, v80, v81
	v_cvt_pk_bf16_f32 v81, v82, v83
	global_store_dwordx2 v[96:97], v[80:81], off offset:64

; DI u32x2 pack4(const f32x4 a) { u32x2 w; w.x = cvt_pk_bf16(a[0], a[1]); w.y = cvt_pk_bf16(a[2], a[3]); return w; }
;     DI void operator()(const pg8::f32x4 (&acc)[2][2][4][2], const pg8::Unit& u, int wr, int wc, int fr, int fq) const {
;     ...
;                 const int r = u.pm * 256 + ai * 128 + wr * 64 + m * 16 + fr;
;                 const int pi = r < MPROMPT ? (r & 2047) : 2048;
;                 const int t = r & 2047;
; #pragma unroll
;                 for (int bj = 0; bj < 2; ++bj) {
;                     const int c0 = pn * 256 + bj * 128 + wc * 32 + 8 * fq;
;                     const f32x4 v0 = acc[ai][bj][m][0] * rsc[ai][m], v1 = acc[ai][bj][m][1] * rsc[ai][m];
;                     if (pn < 4 || (pn == 4 && bj == 0)) {
;                         const int i4 = ((c0 & 63) >> 3) * 4;
;                         const f32x4 cs = *(const f32x4*)(rc + pi * 32 + i4), sn = *(const f32x4*)(rs + pi * 32 + i4);
;                         f32x4 o1 = v0 * cs - v1 * sn, o2 = v1 * cs + v0 * sn;
;                         if (pn < 4) {
;                             o1 = o1 * 0.125f; o2 = o2 * 0.125f;
;                             bf16_t* dst = Q + (size_t)r * AW + (c0 & ~63) + i4;
;                             *(u32x2*)dst = pack4(o1); *(u32x2*)(dst + 32) = pack4(o2);
;                         } else {
;                             const int kvh = (c0 - 1024) >> 6;
;                             bf16_t* dst = Kb + (size_t)r * KVC + kvh * 64 + i4;
;                             *(u32x2*)dst = pack4(o1); *(u32x2*)(dst + 32) = pack4(o2);
;                             float* fo = nullptr;
;                             if (r < MPROMPT) { if (t >= SEQ - 128) fo = kp + ((size_t)((r >> 11) * 128 + (t - (SEQ - 128))) * 2 + kvh) * 64 + i4; }
;                             else if (r < MVALID) fo = ks + ((size_t)((r - MPROMPT) * 128 + 127) * 2 + kvh) * 64 + i4;
;                             if (fo) { *(f32x4*)fo = o1; *(f32x4*)(fo + 32) = o2; }
.LBB0_226:
	s_nop 1
	v_add_u32_e32 v86, s7, v88
	v_lshlrev_b32_e32 v88, 5, v88
	v_lshl_add_u32 v160, v82, 7, v247
	v_ashrrev_i32_e32 v87, 31, v86
	v_cndmask_b32_e64 v88, v248, v88, s[44:45]
	v_lshlrev_b64 v[84:85], 8, v[82:83]
	v_lshlrev_b64 v[82:83], 9, v[160:161]
	v_lshlrev_b64 v[86:87], 9, v[86:87]
	s_andn2_b64 vcc, exec, s[14:15]
	v_lshlrev_b32_e32 v160, 2, v88
	s_cbranch_vccnz .LBB0_233
	v_lshl_add_u64 v[88:89], v[140:141], 0, v[160:161]
	v_mov_b64_e32 v[88:89], v[218:219]
	v_mov_b64_e32 v[90:91], v[220:221]
	v_lshl_add_u64 v[92:93], v[138:139], 0, v[160:161]
	v_mov_b64_e32 v[92:93], v[222:223]
	v_mov_b64_e32 v[94:95], v[224:225]
	s_and_b64 vcc, exec, s[40:41]
	s_mov_b64 s[14:15], -1
	v_pk_mul_f32 v[96:97], v[74:75], v[90:91]
	v_pk_mul_f32 v[98:99], v[72:73], v[88:89]
	v_pk_mul_f32 v[90:91], v[78:79], v[90:91]
	v_pk_mul_f32 v[88:89], v[76:77], v[88:89]
	v_pk_fma_f32 v[78:79], v[78:79], v[94:95], v[96:97] neg_lo:[0,0,1] neg_hi:[0,0,1]
	v_pk_fma_f32 v[76:77], v[76:77], v[92:93], v[98:99] neg_lo:[0,0,1] neg_hi:[0,0,1]
	v_pk_fma_f32 v[74:75], v[74:75], v[94:95], v[90:91]
	v_pk_fma_f32 v[72:73], v[72:73], v[92:93], v[88:89]
	s_cbranch_vccnz .LBB0_231
	v_add_u32_e32 v89, 0xfffffc00, v146
	v_readlane_b32 s14, v253, 19
	v_readlane_b32 s15, v253, 20
	v_and_b32_e32 v92, 0xffffffc0, v89
	v_ashrrev_i32_e32 v93, 31, v92
	v_lshl_add_u64 v[90:91], s[14:15], 0, v[84:85]
	v_lshl_add_u64 v[90:91], v[92:93], 1, v[90:91]
	v_mov_b32_e32 v125, v161
	v_lshl_add_u64 v[90:91], v[90:91], 0, v[124:125]
	v_cvt_pk_bf16_f32 v92, v76, v77
	v_cvt_pk_bf16_f32 v93, v78, v79
	global_store_dwordx2 v[90:91], v[92:93], off
	v_cvt_pk_bf16_f32 v92, v72, v73
	v_cvt_pk_bf16_f32 v93, v74, v75
	v_ashrrev_i32_e32 v88, 6, v89
	global_store_dwordx2 v[90:91], v[92:93], off offset:64
	v_lshl_add_u64 v[90:91], s[52:53], 0, v[86:87]
	v_lshl_add_u64 v[92:93], s[56:57], 0, v[82:83]
	v_ashrrev_i32_e32 v89, 31, v88
	v_cndmask_b32_e64 v91, v93, v91, s[44:45]
	v_cndmask_b32_e64 v90, v92, v90, s[44:45]
	v_cndmask_b32_e64 v92, 0, 1, s[46:47]
	v_cndmask_b32_e64 v93, 0, 1, s[70:71]
	v_lshlrev_b64 v[88:89], 8, v[88:89]
	v_cndmask_b32_e64 v92, v93, v92, s[44:45]
	v_and_b32_e32 v92, 1, v92
	v_lshl_add_u64 v[88:89], v[90:91], 0, v[88:89]
	v_cmp_eq_u32_e32 vcc, 1, v92
	v_cmp_ne_u64_e64 s[48:49], 0, v[88:89]
	s_and_b64 s[24:25], vcc, s[48:49]
	s_and_saveexec_b64 s[14:15], s[24:25]
	s_cbranch_execz .LBB0_230
	v_lshlrev_b32_e32 v90, 2, v136
	v_mov_b32_e32 v91, v161
	v_lshl_add_u64 v[88:89], v[88:89], 0, v[90:91]
	global_store_dwordx4 v[88:89], v[76:79], off
	global_store_dwordx4 v[88:89], v[72:75], off offset:128

; DI u32x2 pack4(const f32x4 a) { u32x2 w; w.x = cvt_pk_bf16(a[0], a[1]); w.y = cvt_pk_bf16(a[2], a[3]); return w; }
;     DI void operator()(const pg8::f32x4 (&acc)[2][2][4][2], const pg8::Unit& u, int wr, int wc, int fr, int fq) const {
;     ...
;                     if (pn < 4 || (pn == 4 && bj == 0)) {
;                         const int i4 = ((c0 & 63) >> 3) * 4;
;                         const f32x4 cs = *(const f32x4*)(rc + pi * 32 + i4), sn = *(const f32x4*)(rs + pi * 32 + i4);
;                         f32x4 o1 = v0 * cs - v1 * sn, o2 = v1 * cs + v0 * sn;
;                         if (pn < 4) {
;                             o1 = o1 * 0.125f; o2 = o2 * 0.125f;
;                             bf16_t* dst = Q + (size_t)r * AW + (c0 & ~63) + i4;
;                             *(u32x2*)dst = pack4(o1); *(u32x2*)(dst + 32) = pack4(o2);
.LBB0_241:
	s_andn2_b64 vcc, exec, s[14:15]
	s_cbranch_vccnz .LBB0_243
	v_lshl_add_u64 v[72:73], v[140:141], 0, v[160:161]
	v_mov_b64_e32 v[72:73], v[218:219]
	v_mov_b64_e32 v[74:75], v[220:221]
	v_lshl_add_u64 v[76:77], v[138:139], 0, v[160:161]
	v_mov_b64_e32 v[76:77], v[222:223]
	v_mov_b64_e32 v[78:79], v[224:225]
	v_lshl_add_u64 v[80:81], s[22:23], 0, v[80:81]
	v_mov_b32_e32 v125, v161
	v_lshl_add_u64 v[80:81], v[122:123], 1, v[80:81]
	v_lshl_add_u64 v[80:81], v[80:81], 0, v[124:125]
	v_pk_mul_f32 v[84:85], v[68:69], v[72:73]
	v_pk_mul_f32 v[72:73], v[64:65], v[72:73]
	v_pk_mul_f32 v[82:83], v[70:71], v[74:75]
	v_pk_mul_f32 v[74:75], v[66:67], v[74:75]
	v_pk_fma_f32 v[64:65], v[64:65], v[76:77], v[84:85]
	v_pk_fma_f32 v[68:69], v[68:69], v[76:77], v[72:73] neg_lo:[0,0,1] neg_hi:[0,0,1]
	v_pk_fma_f32 v[66:67], v[66:67], v[78:79], v[82:83]
	v_pk_fma_f32 v[70:71], v[70:71], v[78:79], v[74:75] neg_lo:[0,0,1] neg_hi:[0,0,1]
	v_pk_mul_f32 v[68:69], v[68:69], s[16:17] op_sel_hi:[1,0]
	v_pk_mul_f32 v[64:65], v[64:65], s[16:17] op_sel_hi:[1,0]
	v_pk_mul_f32 v[70:71], v[70:71], s[16:17] op_sel_hi:[1,0]
	v_pk_mul_f32 v[66:67], v[66:67], s[16:17] op_sel_hi:[1,0]
	v_cvt_pk_bf16_f32 v68, v68, v69
	v_cvt_pk_bf16_f32 v69, v70, v71
	global_store_dwordx2 v[80:81], v[68:69], off
	v_cvt_pk_bf16_f32 v64, v64, v65
	v_cvt_pk_bf16_f32 v65, v66, v67
	global_store_dwordx2 v[80:81], v[64:65], off offset:64

;     DI void operator()(const pg8::f32x4 (&acc)[2][2][4][2], const pg8::Unit& u, int wr, int wc, int fr, int fq) const {
;     ...
;                 const int r = u.pm * 256 + ai * 128 + wr * 64 + m * 16 + fr;
;                 const int pi = r < MPROMPT ? (r & 2047) : 2048;
;                 const int t = r & 2047;
; #pragma unroll
;                 for (int bj = 0; bj < 2; ++bj) {
;                     const int c0 = pn * 256 + bj * 128 + wc * 32 + 8 * fq;
;                     const f32x4 v0 = acc[ai][bj][m][0] * rsc[ai][m], v1 = acc[ai][bj][m][1] * rsc[ai][m];
;                     if (pn < 4 || (pn == 4 && bj == 0)) {
;                         const int i4 = ((c0 & 63) >> 3) * 4;
;                         const f32x4 cs = *(const f32x4*)(rc + pi * 32 + i4), sn = *(const f32x4*)(rs + pi * 32 + i4);
;                         f32x4 o1 = v0 * cs - v1 * sn, o2 = v1 * cs + v0 * sn;
.LBB0_245:
	s_ashr_i32 s7, s6, 4
	s_and_b32 s7, s7, 0xffffff80
	s_addk_i32 s7, 0xf880
	v_lshlrev_b64 v[70:71], 8, v[64:65]
	v_add_u32_e32 v72, s7, v74
	v_lshlrev_b32_e32 v65, 5, v74
	v_lshl_add_u32 v160, v64, 7, v247
	v_ashrrev_i32_e32 v73, 31, v72
	v_cndmask_b32_e64 v65, v248, v65, s[44:45]
	v_lshlrev_b64 v[68:69], 9, v[160:161]
	v_lshlrev_b64 v[72:73], 9, v[72:73]
	s_andn2_b64 vcc, exec, s[14:15]
	v_lshlrev_b32_e32 v160, 2, v65
	s_cbranch_vccnz .LBB0_252
	v_lshl_add_u64 v[74:75], v[140:141], 0, v[160:161]
	v_mov_b32_e32 v235, 0
	v_mov_b32_e32 v237, 0
	v_mov_b32_e32 v239, 0
	v_add_u32_e32 v234, s100, v160
	v_add_u32_e32 v236, s100, v234
	v_add_u32_e32 v238, s100, v236
	v_lshl_add_u64 v[240:241], v[140:141], 0, v[160:161]
	global_load_dwordx4 v[194:197], v[240:241], off
	v_lshl_add_u64 v[240:241], v[138:139], 0, v[160:161]
	global_load_dwordx4 v[198:201], v[240:241], off
	v_lshl_add_u64 v[240:241], v[140:141], 0, v[234:235]
	global_load_dwordx4 v[202:205], v[240:241], off
	v_lshl_add_u64 v[240:241], v[138:139], 0, v[234:235]
	global_load_dwordx4 v[206:209], v[240:241], off
	v_lshl_add_u64 v[240:241], v[140:141], 0, v[236:237]
	global_load_dwordx4 v[210:213], v[240:241], off
	v_lshl_add_u64 v[240:241], v[138:139], 0, v[236:237]
	global_load_dwordx4 v[214:217], v[240:241], off
	v_lshl_add_u64 v[240:241], v[140:141], 0, v[238:239]
	global_load_dwordx4 v[218:221], v[240:241], off
	v_lshl_add_u64 v[240:241], v[138:139], 0, v[238:239]
	global_load_dwordx4 v[222:225], v[240:241], off
	v_lshl_add_u64 v[78:79], v[138:139], 0, v[160:161]
	s_and_b64 vcc, exec, s[40:41]
	s_mov_b64 s[14:15], -1
	s_waitcnt vmcnt(0)
	v_mov_b64_e32 v[74:75], v[194:195]
	v_mov_b64_e32 v[76:77], v[196:197]
	v_mov_b64_e32 v[78:79], v[198:199]
	v_mov_b64_e32 v[80:81], v[200:201]
	v_pk_mul_f32 v[82:83], v[58:59], v[76:77]
	v_pk_mul_f32 v[84:85], v[56:57], v[74:75]
	v_pk_mul_f32 v[76:77], v[62:63], v[76:77]
	v_pk_mul_f32 v[74:75], v[60:61], v[74:75]
	v_pk_fma_f32 v[62:63], v[62:63], v[80:81], v[82:83] neg_lo:[0,0,1] neg_hi:[0,0,1]
	v_pk_fma_f32 v[60:61], v[60:61], v[78:79], v[84:85] neg_lo:[0,0,1] neg_hi:[0,0,1]
	v_pk_fma_f32 v[58:59], v[58:59], v[80:81], v[76:77]
	v_pk_fma_f32 v[56:57], v[56:57], v[78:79], v[74:75]
	s_cbranch_vccnz .LBB0_250
	v_add_u32_e32 v65, 0xfffffc00, v146
	v_readlane_b32 s14, v253, 19
	v_readlane_b32 s15, v253, 20
	v_and_b32_e32 v78, 0xffffffc0, v65
	v_ashrrev_i32_e32 v79, 31, v78
	v_lshl_add_u64 v[76:77], s[14:15], 0, v[70:71]
	v_lshl_add_u64 v[76:77], v[78:79], 1, v[76:77]
	v_mov_b32_e32 v125, v161
	v_lshl_add_u64 v[76:77], v[76:77], 0, v[124:125]
	v_cvt_pk_bf16_f32 v78, v60, v61
	v_cvt_pk_bf16_f32 v79, v62, v63
	global_store_dwordx2 v[76:77], v[78:79], off
	v_cvt_pk_bf16_f32 v78, v56, v57
	v_cvt_pk_bf16_f32 v79, v58, v59
	v_ashrrev_i32_e32 v74, 6, v65
	global_store_dwordx2 v[76:77], v[78:79], off offset:64
	v_lshl_add_u64 v[76:77], s[52:53], 0, v[72:73]
	v_lshl_add_u64 v[78:79], s[56:57], 0, v[68:69]
	v_ashrrev_i32_e32 v75, 31, v74
	v_cndmask_b32_e64 v76, v78, v76, s[44:45]
	v_cndmask_b32_e64 v65, 0, 1, s[46:47]
	v_cndmask_b32_e64 v78, 0, 1, s[70:71]
	v_lshlrev_b64 v[74:75], 8, v[74:75]
	v_cndmask_b32_e64 v77, v79, v77, s[44:45]
	v_cndmask_b32_e64 v65, v78, v65, s[44:45]
	v_and_b32_e32 v65, 1, v65
	v_lshl_add_u64 v[74:75], v[76:77], 0, v[74:75]
	v_cmp_eq_u32_e32 vcc, 1, v65
	v_cmp_ne_u64_e64 s[48:49], 0, v[74:75]
	s_and_b64 s[24:25], vcc, s[48:49]
	s_and_saveexec_b64 s[14:15], s[24:25]
	s_cbranch_execz .LBB0_249
	v_lshlrev_b32_e32 v76, 2, v136
	v_mov_b32_e32 v77, v161
	v_lshl_add_u64 v[74:75], v[74:75], 0, v[76:77]
	global_store_dwordx4 v[74:75], v[60:63], off
	global_store_dwordx4 v[74:75], v[56:59], off offset:128

; DI u32x2 pack4(const f32x4 a) { u32x2 w; w.x = cvt_pk_bf16(a[0], a[1]); w.y = cvt_pk_bf16(a[2], a[3]); return w; }
;     DI void operator()(const pg8::f32x4 (&acc)[2][2][4][2], const pg8::Unit& u, int wr, int wc, int fr, int fq) const {
;     ...
;                     if (pn < 4 || (pn == 4 && bj == 0)) {
;                         const int i4 = ((c0 & 63) >> 3) * 4;
;                         const f32x4 cs = *(const f32x4*)(rc + pi * 32 + i4), sn = *(const f32x4*)(rs + pi * 32 + i4);
;                         f32x4 o1 = v0 * cs - v1 * sn, o2 = v1 * cs + v0 * sn;
;                         if (pn < 4) {
;                             o1 = o1 * 0.125f; o2 = o2 * 0.125f;
;                             bf16_t* dst = Q + (size_t)r * AW + (c0 & ~63) + i4;
;                             *(u32x2*)dst = pack4(o1); *(u32x2*)(dst + 32) = pack4(o2);
.LBB0_260:
	s_andn2_b64 vcc, exec, s[14:15]
	s_cbranch_vccnz .LBB0_262
	v_lshl_add_u64 v[56:57], v[140:141], 0, v[160:161]
	v_mov_b64_e32 v[56:57], v[194:195]
	v_mov_b64_e32 v[58:59], v[196:197]
	v_lshl_add_u64 v[60:61], v[138:139], 0, v[160:161]
	v_mov_b64_e32 v[60:61], v[198:199]
	v_mov_b64_e32 v[62:63], v[200:201]
	v_lshl_add_u64 v[66:67], s[22:23], 0, v[66:67]
	v_mov_b32_e32 v125, v161
	v_lshl_add_u64 v[66:67], v[122:123], 1, v[66:67]
	v_lshl_add_u64 v[66:67], v[66:67], 0, v[124:125]
	v_pk_mul_f32 v[70:71], v[52:53], v[56:57]
	v_pk_mul_f32 v[56:57], v[48:49], v[56:57]
	v_pk_mul_f32 v[68:69], v[54:55], v[58:59]
	v_pk_mul_f32 v[58:59], v[50:51], v[58:59]
	v_pk_fma_f32 v[48:49], v[48:49], v[60:61], v[70:71]
	v_pk_fma_f32 v[52:53], v[52:53], v[60:61], v[56:57] neg_lo:[0,0,1] neg_hi:[0,0,1]
	v_pk_fma_f32 v[50:51], v[50:51], v[62:63], v[68:69]
	v_pk_fma_f32 v[54:55], v[54:55], v[62:63], v[58:59] neg_lo:[0,0,1] neg_hi:[0,0,1]
	v_pk_mul_f32 v[52:53], v[52:53], s[16:17] op_sel_hi:[1,0]
	v_pk_mul_f32 v[48:49], v[48:49], s[16:17] op_sel_hi:[1,0]
	v_pk_mul_f32 v[54:55], v[54:55], s[16:17] op_sel_hi:[1,0]
	v_pk_mul_f32 v[50:51], v[50:51], s[16:17] op_sel_hi:[1,0]
	v_cvt_pk_bf16_f32 v52, v52, v53
	v_cvt_pk_bf16_f32 v53, v54, v55
	global_store_dwordx2 v[66:67], v[52:53], off
	v_cvt_pk_bf16_f32 v48, v48, v49
	v_cvt_pk_bf16_f32 v49, v50, v51
	global_store_dwordx2 v[66:67], v[48:49], off offset:64

; DI u32x2 pack4(const f32x4 a) { u32x2 w; w.x = cvt_pk_bf16(a[0], a[1]); w.y = cvt_pk_bf16(a[2], a[3]); return w; }
;     DI void operator()(const pg8::f32x4 (&acc)[2][2][4][2], const pg8::Unit& u, int wr, int wc, int fr, int fq) const {
;     ...
;                 const int r = u.pm * 256 + ai * 128 + wr * 64 + m * 16 + fr;
;                 const int pi = r < MPROMPT ? (r & 2047) : 2048;
;                 const int t = r & 2047;
; #pragma unroll
;                 for (int bj = 0; bj < 2; ++bj) {
;                     const int c0 = pn * 256 + bj * 128 + wc * 32 + 8 * fq;
;                     const f32x4 v0 = acc[ai][bj][m][0] * rsc[ai][m], v1 = acc[ai][bj][m][1] * rsc[ai][m];
;                     if (pn < 4 || (pn == 4 && bj == 0)) {
;                         const int i4 = ((c0 & 63) >> 3) * 4;
;                         const f32x4 cs = *(const f32x4*)(rc + pi * 32 + i4), sn = *(const f32x4*)(rs + pi * 32 + i4);
;                         f32x4 o1 = v0 * cs - v1 * sn, o2 = v1 * cs + v0 * sn;
;                         if (pn < 4) {
;                             o1 = o1 * 0.125f; o2 = o2 * 0.125f;
;                             bf16_t* dst = Q + (size_t)r * AW + (c0 & ~63) + i4;
;                             *(u32x2*)dst = pack4(o1); *(u32x2*)(dst + 32) = pack4(o2);
;                         } else {
;                             const int kvh = (c0 - 1024) >> 6;
;                             bf16_t* dst = Kb + (size_t)r * KVC + kvh * 64 + i4;
;                             *(u32x2*)dst = pack4(o1); *(u32x2*)(dst + 32) = pack4(o2);
;                             float* fo = nullptr;
;                             if (r < MPROMPT) { if (t >= SEQ - 128) fo = kp + ((size_t)((r >> 11) * 128 + (t - (SEQ - 128))) * 2 + kvh) * 64 + i4; }
;                             else if (r < MVALID) fo = ks + ((size_t)((r - MPROMPT) * 128 + 127) * 2 + kvh) * 64 + i4;
;                             if (fo) { *(f32x4*)fo = o1; *(f32x4*)(fo + 32) = o2; }
.LBB0_264:
	s_nop 1
	v_add_u32_e32 v54, s7, v56
	v_lshlrev_b32_e32 v56, 5, v56
	v_lshl_add_u32 v160, v50, 7, v247
	v_ashrrev_i32_e32 v55, 31, v54
	v_cndmask_b32_e64 v56, v248, v56, s[44:45]
	v_lshlrev_b64 v[52:53], 8, v[50:51]
	v_lshlrev_b64 v[50:51], 9, v[160:161]
	v_lshlrev_b64 v[54:55], 9, v[54:55]
	s_andn2_b64 vcc, exec, s[14:15]
	v_lshlrev_b32_e32 v160, 2, v56
	s_cbranch_vccnz .LBB0_271
	v_lshl_add_u64 v[56:57], v[140:141], 0, v[160:161]
	v_mov_b64_e32 v[56:57], v[202:203]
	v_mov_b64_e32 v[58:59], v[204:205]
	v_lshl_add_u64 v[60:61], v[138:139], 0, v[160:161]
	v_mov_b64_e32 v[60:61], v[206:207]
	v_mov_b64_e32 v[62:63], v[208:209]
	s_and_b64 vcc, exec, s[40:41]
	s_mov_b64 s[14:15], -1
	v_pk_mul_f32 v[64:65], v[42:43], v[58:59]
	v_pk_mul_f32 v[66:67], v[40:41], v[56:57]
	v_pk_mul_f32 v[58:59], v[46:47], v[58:59]
	v_pk_mul_f32 v[56:57], v[44:45], v[56:57]
	v_pk_fma_f32 v[46:47], v[46:47], v[62:63], v[64:65] neg_lo:[0,0,1] neg_hi:[0,0,1]
	v_pk_fma_f32 v[44:45], v[44:45], v[60:61], v[66:67] neg_lo:[0,0,1] neg_hi:[0,0,1]
	v_pk_fma_f32 v[42:43], v[42:43], v[62:63], v[58:59]
	v_pk_fma_f32 v[40:41], v[40:41], v[60:61], v[56:57]
	s_cbranch_vccnz .LBB0_269
	v_add_u32_e32 v57, 0xfffffc00, v146
	v_readlane_b32 s14, v253, 19
	v_readlane_b32 s15, v253, 20
	v_and_b32_e32 v60, 0xffffffc0, v57
	v_ashrrev_i32_e32 v61, 31, v60
	v_lshl_add_u64 v[58:59], s[14:15], 0, v[52:53]
	v_lshl_add_u64 v[58:59], v[60:61], 1, v[58:59]
	v_mov_b32_e32 v125, v161
	v_lshl_add_u64 v[58:59], v[58:59], 0, v[124:125]
	v_cvt_pk_bf16_f32 v60, v44, v45
	v_cvt_pk_bf16_f32 v61, v46, v47
	global_store_dwordx2 v[58:59], v[60:61], off
	v_cvt_pk_bf16_f32 v60, v40, v41
	v_cvt_pk_bf16_f32 v61, v42, v43
	v_ashrrev_i32_e32 v56, 6, v57
	global_store_dwordx2 v[58:59], v[60:61], off offset:64
	v_lshl_add_u64 v[58:59], s[52:53], 0, v[54:55]
	v_lshl_add_u64 v[60:61], s[56:57], 0, v[50:51]
	v_ashrrev_i32_e32 v57, 31, v56
	v_cndmask_b32_e64 v59, v61, v59, s[44:45]
	v_cndmask_b32_e64 v58, v60, v58, s[44:45]
	v_cndmask_b32_e64 v60, 0, 1, s[46:47]
	v_cndmask_b32_e64 v61, 0, 1, s[70:71]
	v_lshlrev_b64 v[56:57], 8, v[56:57]
	v_cndmask_b32_e64 v60, v61, v60, s[44:45]
	v_and_b32_e32 v60, 1, v60
	v_lshl_add_u64 v[56:57], v[58:59], 0, v[56:57]
	v_cmp_eq_u32_e32 vcc, 1, v60
	v_cmp_ne_u64_e64 s[48:49], 0, v[56:57]
	s_and_b64 s[24:25], vcc, s[48:49]
	s_and_saveexec_b64 s[14:15], s[24:25]
	s_cbranch_execz .LBB0_268
	v_lshlrev_b32_e32 v58, 2, v136
	v_mov_b32_e32 v59, v161
	v_lshl_add_u64 v[56:57], v[56:57], 0, v[58:59]
	global_store_dwordx4 v[56:57], v[44:47], off
	global_store_dwordx4 v[56:57], v[40:43], off offset:128

; DI u32x2 pack4(const f32x4 a) { u32x2 w; w.x = cvt_pk_bf16(a[0], a[1]); w.y = cvt_pk_bf16(a[2], a[3]); return w; }
;     DI void operator()(const pg8::f32x4 (&acc)[2][2][4][2], const pg8::Unit& u, int wr, int wc, int fr, int fq) const {
;     ...
;                     if (pn < 4 || (pn == 4 && bj == 0)) {
;                         const int i4 = ((c0 & 63) >> 3) * 4;
;                         const f32x4 cs = *(const f32x4*)(rc + pi * 32 + i4), sn = *(const f32x4*)(rs + pi * 32 + i4);
;                         f32x4 o1 = v0 * cs - v1 * sn, o2 = v1 * cs + v0 * sn;
;                         if (pn < 4) {
;                             o1 = o1 * 0.125f; o2 = o2 * 0.125f;
;                             bf16_t* dst = Q + (size_t)r * AW + (c0 & ~63) + i4;
;                             *(u32x2*)dst = pack4(o1); *(u32x2*)(dst + 32) = pack4(o2);
.LBB0_279:
	s_andn2_b64 vcc, exec, s[14:15]
	s_cbranch_vccnz .LBB0_281
	v_lshl_add_u64 v[40:41], v[140:141], 0, v[160:161]
	v_mov_b64_e32 v[40:41], v[202:203]
	v_mov_b64_e32 v[42:43], v[204:205]
	v_lshl_add_u64 v[44:45], v[138:139], 0, v[160:161]
	v_mov_b64_e32 v[44:45], v[206:207]
	v_mov_b64_e32 v[46:47], v[208:209]
	v_lshl_add_u64 v[48:49], s[22:23], 0, v[48:49]
	v_mov_b32_e32 v125, v161
	v_lshl_add_u64 v[48:49], v[122:123], 1, v[48:49]
	v_lshl_add_u64 v[48:49], v[48:49], 0, v[124:125]
	v_pk_mul_f32 v[52:53], v[36:37], v[40:41]
	v_pk_mul_f32 v[40:41], v[32:33], v[40:41]
	v_pk_mul_f32 v[50:51], v[38:39], v[42:43]
	v_pk_mul_f32 v[42:43], v[34:35], v[42:43]
	v_pk_fma_f32 v[32:33], v[32:33], v[44:45], v[52:53]
	v_pk_fma_f32 v[36:37], v[36:37], v[44:45], v[40:41] neg_lo:[0,0,1] neg_hi:[0,0,1]
	v_pk_fma_f32 v[34:35], v[34:35], v[46:47], v[50:51]
	v_pk_fma_f32 v[38:39], v[38:39], v[46:47], v[42:43] neg_lo:[0,0,1] neg_hi:[0,0,1]
	v_pk_mul_f32 v[36:37], v[36:37], s[16:17] op_sel_hi:[1,0]
	v_pk_mul_f32 v[32:33], v[32:33], s[16:17] op_sel_hi:[1,0]
	v_pk_mul_f32 v[38:39], v[38:39], s[16:17] op_sel_hi:[1,0]
	v_pk_mul_f32 v[34:35], v[34:35], s[16:17] op_sel_hi:[1,0]
	v_cvt_pk_bf16_f32 v36, v36, v37
	v_cvt_pk_bf16_f32 v37, v38, v39
	global_store_dwordx2 v[48:49], v[36:37], off
	v_cvt_pk_bf16_f32 v32, v32, v33
	v_cvt_pk_bf16_f32 v33, v34, v35
	global_store_dwordx2 v[48:49], v[32:33], off offset:64

; DI u32x2 pack4(const f32x4 a) { u32x2 w; w.x = cvt_pk_bf16(a[0], a[1]); w.y = cvt_pk_bf16(a[2], a[3]); return w; }
;     DI void operator()(const pg8::f32x4 (&acc)[2][2][4][2], const pg8::Unit& u, int wr, int wc, int fr, int fq) const {
;     ...
;                 const int r = u.pm * 256 + ai * 128 + wr * 64 + m * 16 + fr;
;                 const int pi = r < MPROMPT ? (r & 2047) : 2048;
;                 const int t = r & 2047;
; #pragma unroll
;                 for (int bj = 0; bj < 2; ++bj) {
;                     const int c0 = pn * 256 + bj * 128 + wc * 32 + 8 * fq;
;                     const f32x4 v0 = acc[ai][bj][m][0] * rsc[ai][m], v1 = acc[ai][bj][m][1] * rsc[ai][m];
;                     if (pn < 4 || (pn == 4 && bj == 0)) {
;                         const int i4 = ((c0 & 63) >> 3) * 4;
;                         const f32x4 cs = *(const f32x4*)(rc + pi * 32 + i4), sn = *(const f32x4*)(rs + pi * 32 + i4);
;                         f32x4 o1 = v0 * cs - v1 * sn, o2 = v1 * cs + v0 * sn;
;                         if (pn < 4) {
;                             o1 = o1 * 0.125f; o2 = o2 * 0.125f;
;                             bf16_t* dst = Q + (size_t)r * AW + (c0 & ~63) + i4;
;                             *(u32x2*)dst = pack4(o1); *(u32x2*)(dst + 32) = pack4(o2);
;                         } else {
;                             const int kvh = (c0 - 1024) >> 6;
;                             bf16_t* dst = Kb + (size_t)r * KVC + kvh * 64 + i4;
;                             *(u32x2*)dst = pack4(o1); *(u32x2*)(dst + 32) = pack4(o2);
;                             float* fo = nullptr;
;                             if (r < MPROMPT) { if (t >= SEQ - 128) fo = kp + ((size_t)((r >> 11) * 128 + (t - (SEQ - 128))) * 2 + kvh) * 64 + i4; }
;                             else if (r < MVALID) fo = ks + ((size_t)((r - MPROMPT) * 128 + 127) * 2 + kvh) * 64 + i4;
;                             if (fo) { *(f32x4*)fo = o1; *(f32x4*)(fo + 32) = o2; }
.LBB0_283:
	s_nop 1
	v_add_u32_e32 v38, s7, v40
	v_lshlrev_b32_e32 v40, 5, v40
	v_lshl_add_u32 v160, v34, 7, v247
	v_ashrrev_i32_e32 v39, 31, v38
	v_cndmask_b32_e64 v40, v248, v40, s[44:45]
	v_lshlrev_b64 v[36:37], 8, v[34:35]
	v_lshlrev_b64 v[34:35], 9, v[160:161]
	v_lshlrev_b64 v[38:39], 9, v[38:39]
	s_andn2_b64 vcc, exec, s[14:15]
	v_lshlrev_b32_e32 v160, 2, v40
	s_cbranch_vccnz .LBB0_290
	v_lshl_add_u64 v[40:41], v[140:141], 0, v[160:161]
	v_mov_b64_e32 v[40:41], v[210:211]
	v_mov_b64_e32 v[42:43], v[212:213]
	v_lshl_add_u64 v[44:45], v[138:139], 0, v[160:161]
	v_mov_b64_e32 v[44:45], v[214:215]
	v_mov_b64_e32 v[46:47], v[216:217]
	s_and_b64 vcc, exec, s[40:41]
	s_mov_b64 s[14:15], -1
	v_pk_mul_f32 v[48:49], v[26:27], v[42:43]
	v_pk_mul_f32 v[50:51], v[24:25], v[40:41]
	v_pk_mul_f32 v[42:43], v[30:31], v[42:43]
	v_pk_mul_f32 v[40:41], v[28:29], v[40:41]
	v_pk_fma_f32 v[30:31], v[30:31], v[46:47], v[48:49] neg_lo:[0,0,1] neg_hi:[0,0,1]
	v_pk_fma_f32 v[28:29], v[28:29], v[44:45], v[50:51] neg_lo:[0,0,1] neg_hi:[0,0,1]
	v_pk_fma_f32 v[26:27], v[26:27], v[46:47], v[42:43]
	v_pk_fma_f32 v[24:25], v[24:25], v[44:45], v[40:41]
	s_cbranch_vccnz .LBB0_288
	v_add_u32_e32 v41, 0xfffffc00, v146
	v_readlane_b32 s14, v253, 19
	v_readlane_b32 s15, v253, 20
	v_and_b32_e32 v44, 0xffffffc0, v41
	v_ashrrev_i32_e32 v45, 31, v44
	v_lshl_add_u64 v[42:43], s[14:15], 0, v[36:37]
	v_lshl_add_u64 v[42:43], v[44:45], 1, v[42:43]
	v_mov_b32_e32 v125, v161
	v_lshl_add_u64 v[42:43], v[42:43], 0, v[124:125]
	v_cvt_pk_bf16_f32 v44, v28, v29
	v_cvt_pk_bf16_f32 v45, v30, v31
	global_store_dwordx2 v[42:43], v[44:45], off
	v_cvt_pk_bf16_f32 v44, v24, v25
	v_cvt_pk_bf16_f32 v45, v26, v27
	v_ashrrev_i32_e32 v40, 6, v41
	global_store_dwordx2 v[42:43], v[44:45], off offset:64
	v_lshl_add_u64 v[42:43], s[52:53], 0, v[38:39]
	v_lshl_add_u64 v[44:45], s[56:57], 0, v[34:35]
	v_ashrrev_i32_e32 v41, 31, v40
	v_cndmask_b32_e64 v43, v45, v43, s[44:45]
	v_cndmask_b32_e64 v42, v44, v42, s[44:45]
	v_cndmask_b32_e64 v44, 0, 1, s[46:47]
	v_cndmask_b32_e64 v45, 0, 1, s[70:71]
	v_lshlrev_b64 v[40:41], 8, v[40:41]
	v_cndmask_b32_e64 v44, v45, v44, s[44:45]
	v_and_b32_e32 v44, 1, v44
	v_lshl_add_u64 v[40:41], v[42:43], 0, v[40:41]
	v_cmp_eq_u32_e32 vcc, 1, v44
	v_cmp_ne_u64_e64 s[48:49], 0, v[40:41]
	s_and_b64 s[24:25], vcc, s[48:49]
	s_and_saveexec_b64 s[14:15], s[24:25]
	s_cbranch_execz .LBB0_287
	v_lshlrev_b32_e32 v42, 2, v136
	v_mov_b32_e32 v43, v161
	v_lshl_add_u64 v[40:41], v[40:41], 0, v[42:43]
	global_store_dwordx4 v[40:41], v[28:31], off
	global_store_dwordx4 v[40:41], v[24:27], off offset:128

; DI u32x2 pack4(const f32x4 a) { u32x2 w; w.x = cvt_pk_bf16(a[0], a[1]); w.y = cvt_pk_bf16(a[2], a[3]); return w; }
;     DI void operator()(const pg8::f32x4 (&acc)[2][2][4][2], const pg8::Unit& u, int wr, int wc, int fr, int fq) const {
;     ...
;                     if (pn < 4 || (pn == 4 && bj == 0)) {
;                         const int i4 = ((c0 & 63) >> 3) * 4;
;                         const f32x4 cs = *(const f32x4*)(rc + pi * 32 + i4), sn = *(const f32x4*)(rs + pi * 32 + i4);
;                         f32x4 o1 = v0 * cs - v1 * sn, o2 = v1 * cs + v0 * sn;
;                         if (pn < 4) {
;                             o1 = o1 * 0.125f; o2 = o2 * 0.125f;
;                             bf16_t* dst = Q + (size_t)r * AW + (c0 & ~63) + i4;
;                             *(u32x2*)dst = pack4(o1); *(u32x2*)(dst + 32) = pack4(o2);
.LBB0_298:
	s_andn2_b64 vcc, exec, s[14:15]
	s_cbranch_vccnz .LBB0_300
	v_lshl_add_u64 v[24:25], v[140:141], 0, v[160:161]
	v_mov_b64_e32 v[24:25], v[210:211]
	v_mov_b64_e32 v[26:27], v[212:213]
	v_lshl_add_u64 v[28:29], v[138:139], 0, v[160:161]
	v_mov_b64_e32 v[28:29], v[214:215]
	v_mov_b64_e32 v[30:31], v[216:217]
	v_lshl_add_u64 v[32:33], s[22:23], 0, v[32:33]
	v_mov_b32_e32 v125, v161
	v_lshl_add_u64 v[32:33], v[122:123], 1, v[32:33]
	v_lshl_add_u64 v[32:33], v[32:33], 0, v[124:125]
	v_pk_mul_f32 v[36:37], v[20:21], v[24:25]
	v_pk_mul_f32 v[24:25], v[16:17], v[24:25]
	v_pk_mul_f32 v[34:35], v[22:23], v[26:27]
	v_pk_mul_f32 v[26:27], v[18:19], v[26:27]
	v_pk_fma_f32 v[16:17], v[16:17], v[28:29], v[36:37]
	v_pk_fma_f32 v[20:21], v[20:21], v[28:29], v[24:25] neg_lo:[0,0,1] neg_hi:[0,0,1]
	v_pk_fma_f32 v[18:19], v[18:19], v[30:31], v[34:35]
	v_pk_fma_f32 v[22:23], v[22:23], v[30:31], v[26:27] neg_lo:[0,0,1] neg_hi:[0,0,1]
	v_pk_mul_f32 v[20:21], v[20:21], s[16:17] op_sel_hi:[1,0]
	v_pk_mul_f32 v[16:17], v[16:17], s[16:17] op_sel_hi:[1,0]
	v_pk_mul_f32 v[22:23], v[22:23], s[16:17] op_sel_hi:[1,0]
	v_pk_mul_f32 v[18:19], v[18:19], s[16:17] op_sel_hi:[1,0]
	v_cvt_pk_bf16_f32 v20, v20, v21
	v_cvt_pk_bf16_f32 v21, v22, v23
	global_store_dwordx2 v[32:33], v[20:21], off
	v_cvt_pk_bf16_f32 v16, v16, v17
	v_cvt_pk_bf16_f32 v17, v18, v19
	global_store_dwordx2 v[32:33], v[16:17], off offset:64

; DI u32x2 pack4(const f32x4 a) { u32x2 w; w.x = cvt_pk_bf16(a[0], a[1]); w.y = cvt_pk_bf16(a[2], a[3]); return w; }
;     DI void operator()(const pg8::f32x4 (&acc)[2][2][4][2], const pg8::Unit& u, int wr, int wc, int fr, int fq) const {
;     ...
;                 const int r = u.pm * 256 + ai * 128 + wr * 64 + m * 16 + fr;
;                 const int pi = r < MPROMPT ? (r & 2047) : 2048;
;                 const int t = r & 2047;
; #pragma unroll
;                 for (int bj = 0; bj < 2; ++bj) {
;                     const int c0 = pn * 256 + bj * 128 + wc * 32 + 8 * fq;
;                     const f32x4 v0 = acc[ai][bj][m][0] * rsc[ai][m], v1 = acc[ai][bj][m][1] * rsc[ai][m];
;                     if (pn < 4 || (pn == 4 && bj == 0)) {
;                         const int i4 = ((c0 & 63) >> 3) * 4;
;                         const f32x4 cs = *(const f32x4*)(rc + pi * 32 + i4), sn = *(const f32x4*)(rs + pi * 32 + i4);
;                         f32x4 o1 = v0 * cs - v1 * sn, o2 = v1 * cs + v0 * sn;
;                         if (pn < 4) {
;                             o1 = o1 * 0.125f; o2 = o2 * 0.125f;
;                             bf16_t* dst = Q + (size_t)r * AW + (c0 & ~63) + i4;
;                             *(u32x2*)dst = pack4(o1); *(u32x2*)(dst + 32) = pack4(o2);
;                         } else {
;                             const int kvh = (c0 - 1024) >> 6;
;                             bf16_t* dst = Kb + (size_t)r * KVC + kvh * 64 + i4;
;                             *(u32x2*)dst = pack4(o1); *(u32x2*)(dst + 32) = pack4(o2);
;                             float* fo = nullptr;
;                             if (r < MPROMPT) { if (t >= SEQ - 128) fo = kp + ((size_t)((r >> 11) * 128 + (t - (SEQ - 128))) * 2 + kvh) * 64 + i4; }
;                             else if (r < MVALID) fo = ks + ((size_t)((r - MPROMPT) * 128 + 127) * 2 + kvh) * 64 + i4;
;                             if (fo) { *(f32x4*)fo = o1; *(f32x4*)(fo + 32) = o2; }
.LBB0_302:
	s_nop 1
	v_add_u32_e32 v22, s7, v24
	v_lshlrev_b32_e32 v24, 5, v24
	v_lshl_add_u32 v160, v18, 7, v247
	v_ashrrev_i32_e32 v23, 31, v22
	v_cndmask_b32_e64 v24, v248, v24, s[44:45]
	v_lshlrev_b64 v[20:21], 8, v[18:19]
	v_lshlrev_b64 v[18:19], 9, v[160:161]
	v_lshlrev_b64 v[22:23], 9, v[22:23]
	s_andn2_b64 vcc, exec, s[14:15]
	v_lshlrev_b32_e32 v160, 2, v24
	s_cbranch_vccnz .LBB0_309
	v_lshl_add_u64 v[24:25], v[140:141], 0, v[160:161]
	v_mov_b64_e32 v[24:25], v[218:219]
	v_mov_b64_e32 v[26:27], v[220:221]
	v_lshl_add_u64 v[28:29], v[138:139], 0, v[160:161]
	v_mov_b64_e32 v[28:29], v[222:223]
	v_mov_b64_e32 v[30:31], v[224:225]
	s_and_b64 vcc, exec, s[40:41]
	s_mov_b64 s[14:15], -1
	v_pk_mul_f32 v[32:33], v[10:11], v[26:27]
	v_pk_mul_f32 v[34:35], v[8:9], v[24:25]
	v_pk_mul_f32 v[26:27], v[14:15], v[26:27]
	v_pk_mul_f32 v[24:25], v[12:13], v[24:25]
	v_pk_fma_f32 v[14:15], v[14:15], v[30:31], v[32:33] neg_lo:[0,0,1] neg_hi:[0,0,1]
	v_pk_fma_f32 v[12:13], v[12:13], v[28:29], v[34:35] neg_lo:[0,0,1] neg_hi:[0,0,1]
	v_pk_fma_f32 v[10:11], v[10:11], v[30:31], v[26:27]
	v_pk_fma_f32 v[8:9], v[8:9], v[28:29], v[24:25]
	s_cbranch_vccnz .LBB0_307
	v_add_u32_e32 v25, 0xfffffc00, v146
	v_readlane_b32 s6, v253, 19
	v_readlane_b32 s7, v253, 20
	v_and_b32_e32 v28, 0xffffffc0, v25
	v_ashrrev_i32_e32 v29, 31, v28
	v_lshl_add_u64 v[26:27], s[6:7], 0, v[20:21]
	v_lshl_add_u64 v[26:27], v[28:29], 1, v[26:27]
	v_mov_b32_e32 v125, v161
	v_lshl_add_u64 v[26:27], v[26:27], 0, v[124:125]
	v_cvt_pk_bf16_f32 v28, v12, v13
	v_cvt_pk_bf16_f32 v29, v14, v15
	global_store_dwordx2 v[26:27], v[28:29], off
	v_cvt_pk_bf16_f32 v28, v8, v9
	v_cvt_pk_bf16_f32 v29, v10, v11
	v_ashrrev_i32_e32 v24, 6, v25
	global_store_dwordx2 v[26:27], v[28:29], off offset:64
	v_lshl_add_u64 v[26:27], s[52:53], 0, v[22:23]
	v_lshl_add_u64 v[28:29], s[56:57], 0, v[18:19]
	v_ashrrev_i32_e32 v25, 31, v24
	v_cndmask_b32_e64 v27, v29, v27, s[44:45]
	v_cndmask_b32_e64 v26, v28, v26, s[44:45]
	v_cndmask_b32_e64 v28, 0, 1, s[46:47]
	v_cndmask_b32_e64 v29, 0, 1, s[48:49]
	v_lshlrev_b64 v[24:25], 8, v[24:25]
	v_cndmask_b32_e64 v28, v29, v28, s[44:45]
	v_and_b32_e32 v28, 1, v28
	v_lshl_add_u64 v[24:25], v[26:27], 0, v[24:25]
	v_cmp_eq_u32_e32 vcc, 1, v28
	v_cmp_ne_u64_e64 s[42:43], 0, v[24:25]
	s_and_b64 s[6:7], vcc, s[42:43]
	s_and_saveexec_b64 s[14:15], s[6:7]
	s_cbranch_execz .LBB0_306
	v_lshlrev_b32_e32 v26, 2, v136
	v_mov_b32_e32 v27, v161
	v_lshl_add_u64 v[24:25], v[24:25], 0, v[26:27]
	global_store_dwordx4 v[24:25], v[12:15], off
	global_store_dwordx4 v[24:25], v[8:11], off offset:128

; DI u32x2 pack4(const f32x4 a) { u32x2 w; w.x = cvt_pk_bf16(a[0], a[1]); w.y = cvt_pk_bf16(a[2], a[3]); return w; }
;     DI void operator()(const pg8::f32x4 (&acc)[2][2][4][2], const pg8::Unit& u, int wr, int wc, int fr, int fq) const {
;     ...
;                     if (pn < 4 || (pn == 4 && bj == 0)) {
;                         const int i4 = ((c0 & 63) >> 3) * 4;
;                         const f32x4 cs = *(const f32x4*)(rc + pi * 32 + i4), sn = *(const f32x4*)(rs + pi * 32 + i4);
;                         f32x4 o1 = v0 * cs - v1 * sn, o2 = v1 * cs + v0 * sn;
;                         if (pn < 4) {
;                             o1 = o1 * 0.125f; o2 = o2 * 0.125f;
;                             bf16_t* dst = Q + (size_t)r * AW + (c0 & ~63) + i4;
;                             *(u32x2*)dst = pack4(o1); *(u32x2*)(dst + 32) = pack4(o2);
.LBB0_319:
	v_lshl_add_u64 v[8:9], v[140:141], 0, v[160:161]
	v_mov_b64_e32 v[8:9], v[218:219]
	v_mov_b64_e32 v[10:11], v[220:221]
	v_lshl_add_u64 v[12:13], v[138:139], 0, v[160:161]
	v_mov_b64_e32 v[12:13], v[222:223]
	v_mov_b64_e32 v[14:15], v[224:225]
	v_lshl_add_u64 v[16:17], s[22:23], 0, v[16:17]
	v_mov_b32_e32 v125, v161
	v_lshl_add_u64 v[16:17], v[122:123], 1, v[16:17]
	v_lshl_add_u64 v[16:17], v[16:17], 0, v[124:125]
	v_pk_mul_f32 v[20:21], v[4:5], v[8:9]
	v_pk_mul_f32 v[8:9], v[0:1], v[8:9]
	v_pk_mul_f32 v[18:19], v[6:7], v[10:11]
	v_pk_mul_f32 v[10:11], v[2:3], v[10:11]
	v_pk_fma_f32 v[0:1], v[0:1], v[12:13], v[20:21]
	v_pk_fma_f32 v[4:5], v[4:5], v[12:13], v[8:9] neg_lo:[0,0,1] neg_hi:[0,0,1]
	v_pk_fma_f32 v[2:3], v[2:3], v[14:15], v[18:19]
	v_pk_fma_f32 v[6:7], v[6:7], v[14:15], v[10:11] neg_lo:[0,0,1] neg_hi:[0,0,1]
	v_pk_mul_f32 v[4:5], v[4:5], s[16:17] op_sel_hi:[1,0]
	v_pk_mul_f32 v[0:1], v[0:1], s[16:17] op_sel_hi:[1,0]
	v_pk_mul_f32 v[6:7], v[6:7], s[16:17] op_sel_hi:[1,0]
	v_pk_mul_f32 v[2:3], v[2:3], s[16:17] op_sel_hi:[1,0]
	v_cvt_pk_bf16_f32 v4, v4, v5
	v_cvt_pk_bf16_f32 v5, v6, v7
	global_store_dwordx2 v[16:17], v[4:5], off
	v_cvt_pk_bf16_f32 v0, v0, v1
	v_cvt_pk_bf16_f32 v1, v2, v3
	global_store_dwordx2 v[16:17], v[0:1], off offset:64
	s_andn2_b64 vcc, exec, s[36:37]
	s_mov_b64 s[14:15], -1
	s_cbranch_vccnz .LBB0_152

; __global__ void __launch_bounds__(NTHREADS, 2) hymba_fwd(Params P) {
	.amdhsa_kernel _Z9hymba_fwd6Params
		.amdhsa_group_segment_fixed_size 0
		.amdhsa_private_segment_fixed_size 0
		.amdhsa_kernarg_size 504
		.amdhsa_user_sgpr_count 2
		.amdhsa_user_sgpr_dispatch_ptr 0
		.amdhsa_user_sgpr_queue_ptr 0
		.amdhsa_user_sgpr_kernarg_segment_ptr 1
		.amdhsa_user_sgpr_dispatch_id 0
		.amdhsa_user_sgpr_kernarg_preload_length 0
		.amdhsa_user_sgpr_kernarg_preload_offset 0
		.amdhsa_user_sgpr_private_segment_size 0
		.amdhsa_uses_dynamic_stack 0
		.amdhsa_enable_private_segment 0
		.amdhsa_system_sgpr_workgroup_id_x 1
		.amdhsa_system_sgpr_workgroup_id_y 0
		.amdhsa_system_sgpr_workgroup_id_z 0
		.amdhsa_system_sgpr_workgroup_info 0
		.amdhsa_system_vgpr_workitem_id 2
		.amdhsa_next_free_vgpr 256
		.amdhsa_next_free_sgpr 102
		.amdhsa_accum_offset 256
		.amdhsa_reserve_vcc 1
		.amdhsa_float_round_mode_32 0
		.amdhsa_float_round_mode_16_64 0
		.amdhsa_float_denorm_mode_32 3
		.amdhsa_float_denorm_mode_16_64 3
		.amdhsa_dx10_clamp 1
		.amdhsa_ieee_mode 1
		.amdhsa_fp16_overflow 0
		.amdhsa_tg_split 0
		.amdhsa_exception_fp_ieee_invalid_op 0
		.amdhsa_exception_fp_denorm_src 0
		.amdhsa_exception_fp_ieee_div_zero 0
		.amdhsa_exception_fp_ieee_overflow 0
		.amdhsa_exception_fp_ieee_underflow 0
		.amdhsa_exception_fp_ieee_inexact 0
		.amdhsa_exception_int_div_zero 0
	.end_amdhsa_kernel

; __global__ void __launch_bounds__(NTHREADS, 2) hymba_fwd(Params P) {
amdhsa.kernels:
  - .agpr_count:     0
    .args:
      - .offset:         0
        .size:           248
        .value_kind:     by_value
      - .offset:         248
        .size:           4
        .value_kind:     hidden_block_count_x
      - .offset:         252
        .size:           4
        .value_kind:     hidden_block_count_y
      - .offset:         256
        .size:           4
        .value_kind:     hidden_block_count_z
      - .offset:         260
        .size:           2
        .value_kind:     hidden_group_size_x
      - .offset:         262
        .size:           2
        .value_kind:     hidden_group_size_y
      - .offset:         264
        .size:           2
        .value_kind:     hidden_group_size_z
      - .offset:         266
        .size:           2
        .value_kind:     hidden_remainder_x
      - .offset:         268
        .size:           2
        .value_kind:     hidden_remainder_y
      - .offset:         270
        .size:           2
        .value_kind:     hidden_remainder_z
      - .offset:         288
        .size:           8
        .value_kind:     hidden_global_offset_x
      - .offset:         296
        .size:           8
        .value_kind:     hidden_global_offset_y
      - .offset:         304
        .size:           8
        .value_kind:     hidden_global_offset_z
      - .offset:         312
        .size:           2
        .value_kind:     hidden_grid_dims
      - .offset:         336
        .size:           8
        .value_kind:     hidden_multigrid_sync_arg
      - .offset:         368
        .size:           4
        .value_kind:     hidden_dynamic_lds_size
    .group_segment_fixed_size: 0
    .kernarg_segment_align: 8
    .kernarg_segment_size: 504
    .language:       OpenCL C
    .language_version:
      - 2
      - 0
    .max_flat_workgroup_size: 512
    .name:           _Z9hymba_fwd6Params
    .private_segment_fixed_size: 0
    .sgpr_count:     108
    .sgpr_spill_count: 287
    .symbol:         _Z9hymba_fwd6Params.kd
    .uniform_work_group_size: 1
    .uses_dynamic_stack: false
    .vgpr_count:     256
    .vgpr_spill_count: 0
    .wavefront_size: 64
